# v25 plus write-through (sc1) stores for the final RMSNorm output so no dirty L2 lines remain at kernel end
# speedup vs baseline: 1.0052x; 1.0031x over previous
; __device__ __forceinline__ float wave_sum(float v) {
; #pragma unroll
;     for (int o = 1; o < 64; o <<= 1) v += __shfl_xor(v, o);
;     return v;
; template <bool FINAL>
; __device__ __forceinline__ void rows_phase(const float* srcL, const float* srcC, int nL, int nTot, const float* g, const float* mod, int sh_off, int sc_off, void* dst, int gw, int NGW, int lane) {
;     ...
;         float ss = 0.f;
; #pragma unroll
;         for (int j = 0; j < 8; ++j) ss += (v[j][0] * v[j][0] + v[j][1] * v[j][1]) + (v[j][2] * v[j][2] + v[j][3] * v[j][3]);
;         const float rstd = 1.0f / sqrtf(wave_sum(ss) * (1.0f / DM) + EPS);
.LBB0_1440:
	v_pk_mul_f32 v[132:133], v[92:93], v[92:93]
	v_pk_mul_f32 v[134:135], v[84:85], v[84:85]
	v_pk_mul_f32 v[128:129], v[94:95], v[94:95]
	v_pk_mul_f32 v[130:131], v[86:87], v[86:87]
	v_mov_b32_e32 v136, v132
	v_mov_b32_e32 v137, v134
	v_mov_b32_e32 v134, v133
	s_waitcnt vmcnt(3)
	v_pk_mul_f32 v[124:125], v[90:91], v[90:91]
	v_pk_mul_f32 v[126:127], v[88:89], v[88:89]
	v_pk_add_f32 v[132:133], v[136:137], v[134:135]
	v_mov_b32_e32 v134, v128
	v_mov_b32_e32 v135, v130
	v_mov_b32_e32 v130, v129
	v_pk_add_f32 v[128:129], v[134:135], v[130:131]
	v_pk_mov_b32 v[130:131], v[126:127], v[124:125] op_sel:[1,0]
	v_mov_b32_e32 v127, v125
	v_pk_add_f32 v[124:125], v[130:131], v[126:127]
	v_pk_add_f32 v[128:129], v[132:133], v[128:129]
	v_pk_add_f32 v[124:125], v[124:125], v[124:125] op_sel_hi:[0,1]
	s_waitcnt vmcnt(2)
	v_mul_f32_e32 v124, v80, v80
	v_pk_fma_f32 v[126:127], v[80:81], v[80:81], v[124:125] op_sel_hi:[1,1,0]
	v_mul_f32_e32 v124, v82, v82
	v_pk_add_f32 v[128:129], v[128:129], v[128:129] op_sel_hi:[0,1]
	v_pk_fma_f32 v[130:131], v[82:83], v[82:83], v[124:125] op_sel_hi:[1,1,0]
	s_waitcnt vmcnt(1)
	v_mul_f32_e32 v126, v76, v76
	v_mul_f32_e32 v130, v77, v77
	v_mul_f32_e32 v124, v78, v78
	v_mul_f32_e32 v128, v79, v79
	s_waitcnt vmcnt(0)
	v_pk_mul_f32 v[120:121], v[74:75], v[74:75]
	v_pk_mul_f32 v[122:123], v[72:73], v[72:73]
	v_pk_add_f32 v[126:127], v[126:127], v[130:131]
	v_pk_add_f32 v[124:125], v[124:125], v[128:129]
	s_nop 0
	v_pk_add_f32 v[124:125], v[126:127], v[124:125]
	v_pk_mov_b32 v[126:127], v[122:123], v[120:121] op_sel:[1,0]
	v_mov_b32_e32 v123, v121
	v_pk_add_f32 v[120:121], v[126:127], v[122:123]
	v_pk_add_f32 v[124:125], v[124:125], v[124:125] op_sel_hi:[0,1]
	v_pk_add_f32 v[120:121], v[120:121], v[120:121] op_sel_hi:[0,1]
	v_mul_f32_e32 v120, v52, v52
	v_pk_fma_f32 v[122:123], v[52:53], v[52:53], v[120:121] op_sel_hi:[1,1,0]
	v_mul_f32_e32 v120, v54, v54
	v_pk_fma_f32 v[126:127], v[54:55], v[54:55], v[120:121] op_sel_hi:[1,1,0]
	v_mul_f32_e32 v122, v116, v116
	v_mul_f32_e32 v126, v117, v117
	v_mul_f32_e32 v120, v118, v118
	v_mul_f32_e32 v124, v119, v119
	v_pk_add_f32 v[116:117], v[122:123], v[126:127]
	v_pk_add_f32 v[118:119], v[120:121], v[124:125]
	s_nop 0
	v_pk_add_f32 v[116:117], v[116:117], v[118:119]
	s_nop 0
	v_add_f32_e32 v116, v116, v117
	ds_bpermute_b32 v117, v110, v116
	s_waitcnt lgkmcnt(0)
	v_add_f32_e32 v116, v116, v117
	ds_bpermute_b32 v117, v111, v116
	s_waitcnt lgkmcnt(0)
	v_add_f32_e32 v116, v116, v117
	ds_bpermute_b32 v117, v112, v116
	s_waitcnt lgkmcnt(0)
	v_add_f32_e32 v116, v116, v117
	ds_bpermute_b32 v117, v113, v116
	s_waitcnt lgkmcnt(0)
	v_add_f32_e32 v116, v116, v117
	ds_bpermute_b32 v117, v114, v116
	s_waitcnt lgkmcnt(0)
	v_add_f32_e32 v116, v116, v117
	ds_bpermute_b32 v117, v115, v116
	s_waitcnt lgkmcnt(0)
; __device__ __forceinline__ unsigned cvtpk(float lo, float hi) { f32x2 v = {lo, hi}; bf16x2_t b = __builtin_convertvector(v, bf16x2_t); return __builtin_bit_cast(unsigned, b); }
; template <bool FINAL>
; __device__ __forceinline__ void rows_phase(const float* srcL, const float* srcC, int nL, int nTot, const float* g, const float* mod, int sh_off, int sc_off, void* dst, int gw, int NGW, int lane) {
;     ...
;         float ss = 0.f;
; #pragma unroll
;         for (int j = 0; j < 8; ++j) ss += (v[j][0] * v[j][0] + v[j][1] * v[j][1]) + (v[j][2] * v[j][2] + v[j][3] * v[j][3]);
;         const float rstd = 1.0f / sqrtf(wave_sum(ss) * (1.0f / DM) + EPS);
; #pragma unroll
;         for (int j = 0; j < 8; ++j) { const int o = j * 256 + lane * 4;
;             if (FINAL) *(f32x4*)((float*)dst + (size_t)row * DM + o) = v[j] * rstd * A[j];
;             else { const f32x4 y = v[j] * rstd * A[j] + B[j]; u32x2 w; w.x = cvtpk(y[0], y[1]); w.y = cvtpk(y[2], y[3]); *(u32x2*)((bf16_t*)dst + (size_t)row * DM + o) = w; } }
;         if (more) {
; #pragma unroll
;             for (int j = 0; j < 8; ++j) v[j] = vn[j]; }
	v_add_f32_e32 v116, v116, v117
	v_fmamk_f32 v116, v116, 0x3a000000, v108
	v_mul_f32_e32 v117, 0x4f800000, v116
	v_cmp_gt_f32_e32 vcc, s7, v116
	s_nop 1
	v_cndmask_b32_e32 v116, v116, v117, vcc
	v_sqrt_f32_e32 v117, v116
	s_nop 0
	v_add_u32_e32 v118, -1, v117
	v_fma_f32 v119, -v118, v117, v116
	v_cmp_ge_f32_e64 s[0:1], 0, v119
	v_add_u32_e32 v119, 1, v117
	s_nop 0
	v_cndmask_b32_e64 v118, v117, v118, s[0:1]
	v_fma_f32 v117, -v119, v117, v116
	v_cmp_lt_f32_e64 s[0:1], 0, v117
	s_nop 1
	v_cndmask_b32_e64 v117, v118, v119, s[0:1]
	v_mul_f32_e32 v118, 0x37800000, v117
	v_cndmask_b32_e32 v117, v117, v118, vcc
	v_cmp_class_f32_e32 vcc, v116, v109
	s_nop 1
	v_cndmask_b32_e32 v116, v117, v116, vcc
	v_div_scale_f32 v117, s[0:1], v116, v116, 1.0
	v_rcp_f32_e32 v118, v117
	s_mov_b64 s[0:1], -1
	v_fma_f32 v119, -v117, v118, 1.0
	v_fmac_f32_e32 v118, v119, v118
	v_div_scale_f32 v119, vcc, 1.0, v116, 1.0
	v_mul_f32_e32 v120, v119, v118
	v_fma_f32 v121, -v117, v120, v119
	v_fmac_f32_e32 v120, v121, v118
	v_fma_f32 v117, -v117, v120, v119
	v_div_fmas_f32 v117, v117, v118, v120
	v_div_fixup_f32 v116, v117, v116, 1.0
	v_pk_mul_f32 v[80:81], v[80:81], v[116:117] op_sel_hi:[1,0]
	v_pk_mul_f32 v[82:83], v[82:83], v[116:117] op_sel_hi:[1,0]
	v_pk_mul_f32 v[84:85], v[84:85], v[116:117] op_sel_hi:[1,0]
	v_pk_mul_f32 v[86:87], v[86:87], v[116:117] op_sel_hi:[1,0]
	v_pk_mul_f32 v[82:83], v[22:23], v[82:83]
	v_pk_mul_f32 v[80:81], v[20:21], v[80:81]
	v_pk_mul_f32 v[86:87], v[30:31], v[86:87]
	v_pk_mul_f32 v[84:85], v[28:29], v[84:85]
	global_store_dwordx4 v[96:97], v[80:83], off offset:3072 sc1
	v_pk_mul_f32 v[0:1], v[0:1], v[116:117] op_sel_hi:[1,0]
	v_pk_mul_f32 v[2:3], v[2:3], v[116:117] op_sel_hi:[1,0]
	v_add_co_u32_e32 v80, vcc, s6, v96
	v_pk_mul_f32 v[92:93], v[92:93], v[116:117] op_sel_hi:[1,0]
	v_pk_mul_f32 v[94:95], v[94:95], v[116:117] op_sel_hi:[1,0]
	global_store_dwordx4 v[96:97], v[84:87], off offset:1024 sc1
	v_pk_mul_f32 v[76:77], v[76:77], v[116:117] op_sel_hi:[1,0]
	v_pk_mul_f32 v[78:79], v[78:79], v[116:117] op_sel_hi:[1,0]
	v_pk_mul_f32 v[84:85], v[88:89], v[116:117] op_sel_hi:[1,0]
	v_pk_mul_f32 v[86:87], v[90:91], v[116:117] op_sel_hi:[1,0]
	v_addc_co_u32_e32 v81, vcc, 0, v97, vcc
	v_pk_mul_f32 v[72:73], v[72:73], v[116:117] op_sel_hi:[1,0]
	v_pk_mul_f32 v[74:75], v[74:75], v[116:117] op_sel_hi:[1,0]
	v_pk_mul_f32 v[52:53], v[52:53], v[116:117] op_sel_hi:[1,0]
	v_pk_mul_f32 v[54:55], v[54:55], v[116:117] op_sel_hi:[1,0]
	v_pk_mul_f32 v[2:3], v[6:7], v[2:3]
	v_pk_mul_f32 v[0:1], v[4:5], v[0:1]
	v_pk_mul_f32 v[94:95], v[34:35], v[94:95]
	v_pk_mul_f32 v[92:93], v[32:33], v[92:93]
	v_pk_mul_f32 v[86:87], v[26:27], v[86:87]
	v_pk_mul_f32 v[84:85], v[24:25], v[84:85]
	v_pk_mul_f32 v[78:79], v[18:19], v[78:79]
	v_pk_mul_f32 v[76:77], v[16:17], v[76:77]
	v_pk_mul_f32 v[74:75], v[14:15], v[74:75]
	v_pk_mul_f32 v[72:73], v[12:13], v[72:73]
	v_pk_mul_f32 v[54:55], v[10:11], v[54:55]
	v_pk_mul_f32 v[52:53], v[8:9], v[52:53]
	global_store_dwordx4 v[80:81], v[0:3], off offset:3072 sc1
	global_store_dwordx4 v[96:97], v[92:95], off sc1
	global_store_dwordx4 v[96:97], v[84:87], off offset:2048 sc1
	v_mov_b64_e32 v[0:1], v[56:57]
	global_store_dwordx4 v[80:81], v[76:79], off sc1
	global_store_dwordx4 v[80:81], v[72:75], off offset:1024 sc1
	global_store_dwordx4 v[80:81], v[52:55], off offset:2048 sc1
	v_lshl_add_u64 v[96:97], v[96:97], 0, s[2:3]
	s_andn2_b64 vcc, exec, s[4:5]
	v_mov_b64_e32 v[2:3], v[58:59]
	v_mov_b32_e32 v92, v48
	v_mov_b32_e32 v93, v49
	v_mov_b32_e32 v94, v50
	v_mov_b32_e32 v95, v51
	v_mov_b32_e32 v84, v44
	v_mov_b32_e32 v85, v45
	v_mov_b32_e32 v86, v46
	v_mov_b32_e32 v87, v47
	v_mov_b32_e32 v88, v40
	v_mov_b32_e32 v89, v41
	v_mov_b32_e32 v90, v42
	v_mov_b32_e32 v91, v43
	v_mov_b32_e32 v80, v36
	v_mov_b32_e32 v81, v37
	v_mov_b32_e32 v82, v38
	v_mov_b32_e32 v83, v39
	v_mov_b32_e32 v76, v68
	v_mov_b32_e32 v77, v69
	v_mov_b32_e32 v78, v70
	v_mov_b32_e32 v79, v71
	v_mov_b32_e32 v72, v64
	v_mov_b32_e32 v73, v65
	v_mov_b32_e32 v74, v66
	v_mov_b32_e32 v75, v67
	v_mov_b32_e32 v52, v60
	v_mov_b32_e32 v53, v61
	v_mov_b32_e32 v54, v62
	v_mov_b32_e32 v55, v63
	v_mov_b32_e32 v116, v56
	v_mov_b32_e32 v117, v57
	v_mov_b32_e32 v118, v58
	v_mov_b32_e32 v119, v59
	s_cbranch_vccz .LBB0_1445
